# P3 scan: per-step o-buffer stores marked nt
# baseline (speedup 1.0000x reference)
.LBB0_888:
	ds_read_b128 v[246:249], v237
	v_lshl_add_u64 v[214:215], s[8:9], 0, v[196:197]
	v_add_co_u32_e32 v98, vcc, s25, v214
	v_lshl_add_u64 v[216:217], s[8:9], 0, v[198:199]
	s_nop 0
	v_addc_co_u32_e32 v99, vcc, 0, v215, vcc
	v_add_co_u32_e32 v102, vcc, s26, v214
	v_lshl_add_u64 v[218:219], s[8:9], 0, v[200:201]
	s_nop 0
	v_addc_co_u32_e32 v103, vcc, 0, v215, vcc
	v_add_co_u32_e32 v106, vcc, s25, v216
	v_lshl_add_u64 v[220:221], s[8:9], 0, v[202:203]
	s_nop 0
	v_addc_co_u32_e32 v107, vcc, 0, v217, vcc
	v_add_co_u32_e32 v110, vcc, s26, v216
	v_lshl_add_u64 v[222:223], s[8:9], 0, v[194:195]
	s_nop 0
	v_addc_co_u32_e32 v111, vcc, 0, v217, vcc
	v_add_co_u32_e32 v114, vcc, s25, v218
	v_lshl_add_u64 v[224:225], s[8:9], 0, v[204:205]
	s_nop 0
	v_addc_co_u32_e32 v115, vcc, 0, v219, vcc
	v_add_co_u32_e32 v118, vcc, s26, v218
	global_load_dwordx4 v[98:101], v[98:99], off
	s_nop 0
	v_addc_co_u32_e32 v119, vcc, 0, v219, vcc
	v_add_co_u32_e32 v122, vcc, s25, v220
	global_load_dwordx4 v[102:105], v[102:103], off
	s_nop 0
	v_addc_co_u32_e32 v123, vcc, 0, v221, vcc
	v_add_co_u32_e32 v126, vcc, s26, v220
	global_load_dwordx4 v[106:109], v[106:107], off
	s_nop 0
	v_addc_co_u32_e32 v127, vcc, 0, v221, vcc
	v_add_co_u32_e32 v130, vcc, s27, v222
	global_load_dwordx4 v[110:113], v[110:111], off
	s_nop 0
	v_addc_co_u32_e32 v131, vcc, 0, v223, vcc
	global_load_dwordx4 v[114:117], v[114:115], off
	v_lshl_add_u64 v[226:227], s[8:9], 0, v[206:207]
	global_load_dwordx4 v[118:121], v[118:119], off
	v_lshl_add_u64 v[228:229], s[8:9], 0, v[208:209]
	global_load_dwordx4 v[122:125], v[122:123], off
	v_lshl_add_u64 v[230:231], s[8:9], 0, v[210:211]
	global_load_dwordx4 v[126:129], v[126:127], off
	s_nop 0
	global_load_dword v241, v[130:131], off
	global_load_dword v242, v[130:131], off offset:256
	global_load_dword v243, v[130:131], off offset:512
	global_load_dword v244, v[130:131], off offset:768
	v_add_co_u32_e32 v130, vcc, s34, v224
	v_lshl_add_u64 v[232:233], s[8:9], 0, v[212:213]
	s_nop 0
	v_addc_co_u32_e32 v131, vcc, 0, v225, vcc
	v_add_co_u32_e32 v134, vcc, s34, v226
	global_load_dwordx4 v[130:133], v[130:131], off
	s_nop 0
	v_addc_co_u32_e32 v135, vcc, 0, v227, vcc
	v_add_co_u32_e32 v146, vcc, s35, v228
	global_load_dwordx4 v[134:137], v[134:135], off
	s_nop 0
	v_addc_co_u32_e32 v147, vcc, 0, v229, vcc
	v_add_co_u32_e32 v142, vcc, s35, v230
	global_load_dwordx4 v[138:141], v[146:147], off
	s_nop 0
	v_addc_co_u32_e32 v143, vcc, 0, v231, vcc
	global_load_dwordx4 v[142:145], v[142:143], off
	s_nop 0
	global_load_dwordx4 v[146:149], v[146:147], off offset:1024

	s_waitcnt vmcnt(37) lgkmcnt(0)
	v_mfma_f32_16x16x32_bf16 v[18:21], v[18:21], v[246:249], 0
	v_add_co_u32_e32 v150, vcc, s35, v232
	s_add_i32 s61, s62, 6
	s_waitcnt vmcnt(31)
	v_mfma_f32_16x16x32_bf16 v[38:41], v[38:41], v[246:249], 0
	ds_read_b128 v[246:249], v237 offset:64
	v_addc_co_u32_e32 v151, vcc, 0, v233, vcc
	s_waitcnt lgkmcnt(0)
	v_mfma_f32_16x16x32_bf16 v[6:9], v[6:9], v[246:249], v[18:21]
	global_load_dwordx4 v[150:153], v[150:151], off
	s_nop 1
	ds_read_b128 v[18:21], v237 offset:128
	s_add_i32 s65, s62, 7
	v_mfma_f32_16x16x32_bf16 v[2:5], v[2:5], v[246:249], v[38:41]
	v_readlane_b32 s64, v177, s61
	v_readlane_b32 s66, v177, s65
	s_add_i32 s63, s62, 8
	s_waitcnt vmcnt(27) lgkmcnt(0)
	v_mfma_f32_16x16x32_bf16 v[2:5], v[14:17], v[18:21], v[2:5]
	ds_read_b128 v[14:17], v237 offset:192
	v_lshl_add_u64 v[194:195], v[194:195], 0, s[16:17]
	v_lshl_add_u64 v[196:197], v[196:197], 0, s[18:19]
	s_waitcnt vmcnt(21)
	v_mfma_f32_16x16x32_bf16 v[6:9], v[26:29], v[18:21], v[6:9]
	v_mul_f32_e64 v20, v92, s64
	v_mul_f32_e64 v21, v93, s64
	v_pk_mul_f32 v[18:19], v[90:91], s[64:65] op_sel_hi:[1,0]
	v_lshl_add_u64 v[198:199], v[198:199], 0, s[18:19]
	s_waitcnt vmcnt(19) lgkmcnt(0)
	v_mfma_f32_16x16x32_bf16 v[6:9], v[22:25], v[14:17], v[6:9]
	v_lshl_add_u64 v[200:201], v[200:201], 0, s[18:19]
	v_lshl_add_u64 v[202:203], v[202:203], 0, s[18:19]
	v_lshl_add_u64 v[204:205], v[204:205], 0, s[20:21]
	v_mfma_f32_16x16x32_bf16 v[2:5], v[10:13], v[14:17], v[2:5]
	v_mul_f32_e64 v16, v96, s64
	v_mul_f32_e64 v17, v97, s64
	s_nop 1
	v_sub_f32_e32 v9, v240, v9
	v_sub_f32_e32 v8, v239, v8
	v_sub_f32_e32 v7, v238, v7
	v_sub_f32_e32 v6, v193, v6
	v_cvt_pk_bf16_f32 v6, v6, v7
	v_cvt_pk_bf16_f32 v7, v8, v9
	ds_write_b64 v236, v[6:7] offset:4352
	s_waitcnt lgkmcnt(0)
	s_barrier
	ds_read_b128 v[6:9], v235 offset:4352
	ds_read_b128 v[10:13], v235 offset:4416
	v_pk_mul_f32 v[14:15], v[94:95], s[64:65] op_sel_hi:[1,0]
	s_waitcnt lgkmcnt(1)
	v_mfma_f32_16x16x32_bf16 v[2:5], v[86:89], v[6:9], v[2:5]
	v_ashrrev_i32_e32 v193, 31, v192
	s_add_i32 s64, s62, 9
	s_add_i32 s65, s62, 10
	v_mfma_f32_16x16x32_bf16 v[14:17], v[70:73], v[6:9], v[14:17]
	v_readlane_b32 s64, v177, s64
	s_add_i32 s62, s62, 11
	v_readlane_b32 s62, v177, s62
	v_mfma_f32_16x16x32_bf16 v[6:9], v[66:69], v[6:9], v[18:21]
	v_lshl_add_u64 v[206:207], v[206:207], 0, s[20:21]
	v_lshl_add_u64 v[208:209], v[208:209], 0, s[18:19]
	v_lshl_add_u64 v[210:211], v[210:211], 0, s[18:19]
	s_waitcnt lgkmcnt(0)
	v_mfma_f32_16x16x32_bf16 v[90:93], v[82:85], v[10:13], v[14:17]
	v_lshl_add_u64 v[212:213], v[212:213], 0, s[18:19]
	s_cmp_lt_u32 s61, 24
	v_mfma_f32_16x16x32_bf16 v[94:97], v[78:81], v[10:13], v[6:9]
	v_mfma_f32_16x16x32_bf16 v[2:5], v[74:77], v[10:13], v[2:5]
	s_nop 3
	v_cvt_pk_bf16_f32 v6, v90, v91
	v_cvt_pk_bf16_f32 v7, v92, v93
	s_nop 0
	v_cvt_pk_bf16_f32 v8, v94, v95
	v_cvt_pk_bf16_f32 v9, v96, v97
	ds_write2_b64 v234, v[6:7], v[8:9] offset1:4
	v_lshlrev_b64 v[6:7], 12, v[192:193]
	v_lshl_add_u64 v[6:7], v[190:191], 0, v[6:7]
	v_add_co_u32_e32 v8, vcc, s30, v6
	global_store_dword v[6:7], v2, off nt
	s_nop 0
	v_addc_co_u32_e32 v9, vcc, 0, v7, vcc
	v_add_co_u32_e32 v2, vcc, s31, v6
	global_store_dword v[8:9], v3, off offset:-4096 nt
	global_store_dword v[8:9], v4, off nt
	v_addc_co_u32_e32 v3, vcc, 0, v7, vcc
	global_store_dword v[2:3], v5, off nt
	v_add_co_u32_e32 v2, vcc, s36, v214
	s_waitcnt lgkmcnt(0)
	s_barrier
	ds_read_b128 v[246:249], v237
	s_nop 0
	v_addc_co_u32_e32 v3, vcc, 0, v215, vcc
	v_add_co_u32_e32 v6, vcc, s37, v214
	global_load_dwordx4 v[2:5], v[2:3], off
	s_nop 0
	v_addc_co_u32_e32 v7, vcc, 0, v215, vcc
	v_add_co_u32_e32 v10, vcc, s36, v216
	global_load_dwordx4 v[6:9], v[6:7], off
	s_nop 0
	v_addc_co_u32_e32 v11, vcc, 0, v217, vcc
	v_add_co_u32_e32 v14, vcc, s37, v216
	global_load_dwordx4 v[10:13], v[10:11], off
	s_nop 0
	v_addc_co_u32_e32 v15, vcc, 0, v217, vcc
	v_add_co_u32_e32 v18, vcc, s36, v218
	global_load_dwordx4 v[14:17], v[14:15], off
	s_nop 0
	v_addc_co_u32_e32 v19, vcc, 0, v219, vcc
	v_add_co_u32_e32 v22, vcc, s37, v218
	global_load_dwordx4 v[18:21], v[18:19], off
	s_nop 0
	v_addc_co_u32_e32 v23, vcc, 0, v219, vcc
	v_add_co_u32_e32 v26, vcc, s36, v220
	global_load_dwordx4 v[22:25], v[22:23], off
	s_nop 0
	v_addc_co_u32_e32 v27, vcc, 0, v221, vcc
	v_add_co_u32_e32 v38, vcc, s37, v220
	global_load_dwordx4 v[26:29], v[26:27], off
	s_nop 0
	v_addc_co_u32_e32 v39, vcc, 0, v221, vcc
	v_add_co_u32_e32 v66, vcc, s38, v222
	global_load_dwordx4 v[38:41], v[38:39], off
	s_nop 0
	v_addc_co_u32_e32 v67, vcc, 0, v223, vcc
	global_load_dword v193, v[66:67], off
	global_load_dword v238, v[66:67], off offset:256
	global_load_dword v239, v[66:67], off offset:512
	global_load_dword v240, v[66:67], off offset:768
	v_add_co_u32_e32 v66, vcc, s39, v224
	s_nop 1
	v_addc_co_u32_e32 v67, vcc, 0, v225, vcc
	v_add_co_u32_e32 v70, vcc, s39, v226
	global_load_dwordx4 v[66:69], v[66:67], off
	s_nop 0
	v_addc_co_u32_e32 v71, vcc, 0, v227, vcc
	v_add_co_u32_e32 v82, vcc, s40, v228
	global_load_dwordx4 v[74:77], v[70:71], off
	s_nop 0
	v_addc_co_u32_e32 v83, vcc, 0, v229, vcc
	v_add_co_u32_e32 v78, vcc, s40, v230
	global_load_dwordx4 v[70:73], v[82:83], off
	s_nop 0
	v_addc_co_u32_e32 v79, vcc, 0, v231, vcc
	global_load_dwordx4 v[78:81], v[78:79], off
	s_nop 0
	global_load_dwordx4 v[82:85], v[82:83], off offset:1024

	s_waitcnt lgkmcnt(0)
	v_mfma_f32_16x16x32_bf16 v[30:33], v[30:33], v[246:249], 0
	v_add_co_u32_e32 v86, vcc, s40, v232
	v_mfma_f32_16x16x32_bf16 v[34:37], v[34:37], v[246:249], 0
	ds_read_b128 v[246:249], v237 offset:64
	v_addc_co_u32_e32 v87, vcc, 0, v233, vcc
	s_waitcnt lgkmcnt(0)
	v_mfma_f32_16x16x32_bf16 v[30:33], v[46:49], v[246:249], v[30:33]
	ds_read_b128 v[46:49], v237 offset:128
	global_load_dwordx4 v[86:89], v[86:87], off
	s_waitcnt lgkmcnt(0)
	v_mfma_f32_16x16x32_bf16 v[30:33], v[42:45], v[46:49], v[30:33]
	ds_read_b128 v[42:45], v237 offset:192
	v_mfma_f32_16x16x32_bf16 v[34:37], v[50:53], v[246:249], v[34:37]
	v_mul_f32_e64 v52, v96, s66
	v_mul_f32_e64 v53, v97, s66
	v_pk_mul_f32 v[50:51], v[94:95], s[66:67] op_sel_hi:[1,0]
	s_waitcnt lgkmcnt(0)
	v_mfma_f32_16x16x32_bf16 v[30:33], v[58:61], v[42:45], v[30:33]
	v_mfma_f32_16x16x32_bf16 v[34:37], v[54:57], v[46:49], v[34:37]
	v_mul_f32_e64 v48, v92, s66
	v_mul_f32_e64 v49, v93, s66
	s_nop 4
	v_sub_f32_e32 v33, v156, v33
	v_sub_f32_e32 v32, v155, v32
	v_sub_f32_e32 v31, v154, v31
	s_waitcnt vmcnt(40)
	v_sub_f32_e32 v30, v157, v30
	v_cvt_pk_bf16_f32 v30, v30, v31
	v_cvt_pk_bf16_f32 v31, v32, v33
	ds_write_b64 v236, v[30:31] offset:4352
	s_waitcnt lgkmcnt(0)
	s_barrier
	v_mfma_f32_16x16x32_bf16 v[34:37], v[62:65], v[42:45], v[34:37]
	ds_read_b128 v[30:33], v235 offset:4352
	ds_read_b128 v[42:45], v235 offset:4416
	v_pk_mul_f32 v[46:47], v[90:91], s[66:67] op_sel_hi:[1,0]
	v_readlane_b32 s66, v177, s63
	s_waitcnt vmcnt(27) lgkmcnt(1)
	v_mfma_f32_16x16x32_bf16 v[34:37], v[130:133], v[30:33], v[34:37]
	s_waitcnt vmcnt(25)
	v_mfma_f32_16x16x32_bf16 v[46:49], v[138:141], v[30:33], v[46:49]
	s_waitcnt vmcnt(23)
	v_mfma_f32_16x16x32_bf16 v[30:33], v[146:149], v[30:33], v[50:53]
	s_waitcnt lgkmcnt(0)
	v_mfma_f32_16x16x32_bf16 v[90:93], v[142:145], v[42:45], v[46:49]
	s_waitcnt vmcnt(22)
	v_mfma_f32_16x16x32_bf16 v[94:97], v[150:153], v[42:45], v[30:33]
	v_mfma_f32_16x16x32_bf16 v[34:37], v[134:137], v[42:45], v[34:37]
	s_nop 4
	v_cvt_pk_bf16_f32 v30, v90, v91
	v_cvt_pk_bf16_f32 v31, v92, v93
	v_cvt_pk_bf16_f32 v32, v94, v95
	v_cvt_pk_bf16_f32 v33, v96, v97
	ds_write2_b64 v234, v[30:31], v[32:33] offset1:4
	v_add_u32_e32 v30, 64, v192
	v_ashrrev_i32_e32 v31, 31, v30
	v_lshlrev_b64 v[30:31], 12, v[30:31]
	v_lshl_add_u64 v[30:31], v[190:191], 0, v[30:31]
	v_add_co_u32_e32 v32, vcc, s30, v30
	global_store_dword v[30:31], v34, off nt
	s_nop 0
	v_addc_co_u32_e32 v33, vcc, 0, v31, vcc
	v_add_co_u32_e32 v30, vcc, s31, v30
	global_store_dword v[32:33], v35, off offset:-4096 nt
	global_store_dword v[32:33], v36, off nt
	v_addc_co_u32_e32 v31, vcc, 0, v31, vcc
	global_store_dword v[30:31], v37, off nt
	v_add_co_u32_e32 v30, vcc, s41, v214
	s_waitcnt lgkmcnt(0)
	s_barrier
	ds_read_b128 v[154:157], v237
	s_nop 0
	v_addc_co_u32_e32 v31, vcc, 0, v215, vcc
	v_add_co_u32_e32 v34, vcc, s42, v214
	global_load_dwordx4 v[30:33], v[30:31], off
	s_nop 0
	v_addc_co_u32_e32 v35, vcc, 0, v215, vcc
	v_add_co_u32_e32 v42, vcc, s41, v216
	global_load_dwordx4 v[34:37], v[34:35], off
	s_nop 0
	v_addc_co_u32_e32 v43, vcc, 0, v217, vcc
	v_add_co_u32_e32 v46, vcc, s42, v216
	global_load_dwordx4 v[42:45], v[42:43], off
	s_nop 0
	v_addc_co_u32_e32 v47, vcc, 0, v217, vcc
	v_add_co_u32_e32 v50, vcc, s41, v218
	global_load_dwordx4 v[46:49], v[46:47], off
	s_nop 0
	v_addc_co_u32_e32 v51, vcc, 0, v219, vcc
	v_add_co_u32_e32 v54, vcc, s42, v218
	global_load_dwordx4 v[50:53], v[50:51], off
	s_nop 0
	v_addc_co_u32_e32 v55, vcc, 0, v219, vcc
	v_add_co_u32_e32 v58, vcc, s41, v220
	global_load_dwordx4 v[54:57], v[54:55], off
	s_nop 0
	v_addc_co_u32_e32 v59, vcc, 0, v221, vcc
	v_add_co_u32_e32 v62, vcc, s42, v220
	global_load_dwordx4 v[58:61], v[58:59], off
	s_nop 0
	v_addc_co_u32_e32 v63, vcc, 0, v221, vcc
	v_add_co_u32_e32 v130, vcc, s43, v222
	global_load_dwordx4 v[62:65], v[62:63], off
	s_nop 0
	v_addc_co_u32_e32 v131, vcc, 0, v223, vcc
	global_load_dword v245, v[130:131], off
	global_load_dword v246, v[130:131], off offset:256
	global_load_dword v247, v[130:131], off offset:512
	global_load_dword v248, v[130:131], off offset:768
	v_add_co_u32_e32 v130, vcc, s44, v224
	s_nop 1
	v_addc_co_u32_e32 v131, vcc, 0, v225, vcc
	v_add_co_u32_e32 v134, vcc, s44, v226
	global_load_dwordx4 v[130:133], v[130:131], off
	s_nop 0
	v_addc_co_u32_e32 v135, vcc, 0, v227, vcc
	v_add_co_u32_e32 v146, vcc, s45, v228
	global_load_dwordx4 v[138:141], v[134:135], off
	s_nop 0
	v_addc_co_u32_e32 v147, vcc, 0, v229, vcc
	v_add_co_u32_e32 v142, vcc, s45, v230
	global_load_dwordx4 v[134:137], v[146:147], off
	s_nop 0
	v_addc_co_u32_e32 v143, vcc, 0, v231, vcc
	global_load_dwordx4 v[142:145], v[142:143], off
	s_nop 0
	global_load_dwordx4 v[146:149], v[146:147], off offset:1024

	s_waitcnt lgkmcnt(0)
	v_mfma_f32_16x16x32_bf16 v[98:101], v[98:101], v[154:157], 0
	v_add_co_u32_e32 v150, vcc, s45, v232
	v_mfma_f32_16x16x32_bf16 v[102:105], v[102:105], v[154:157], 0
	ds_read_b128 v[154:157], v237 offset:64
	v_addc_co_u32_e32 v151, vcc, 0, v233, vcc
	s_waitcnt lgkmcnt(0)
	v_mfma_f32_16x16x32_bf16 v[98:101], v[106:109], v[154:157], v[98:101]
	ds_read_b128 v[106:109], v237 offset:128
	global_load_dwordx4 v[150:153], v[150:151], off
	v_mfma_f32_16x16x32_bf16 v[102:105], v[110:113], v[154:157], v[102:105]
	s_waitcnt lgkmcnt(0)
	v_mfma_f32_16x16x32_bf16 v[98:101], v[114:117], v[106:109], v[98:101]
	v_mfma_f32_16x16x32_bf16 v[102:105], v[118:121], v[106:109], v[102:105]
	ds_read_b128 v[106:109], v237 offset:192
	s_waitcnt lgkmcnt(0)
	v_mfma_f32_16x16x32_bf16 v[98:101], v[122:125], v[106:109], v[98:101]
	v_mfma_f32_16x16x32_bf16 v[102:105], v[126:129], v[106:109], v[102:105]
	s_nop 6
	v_sub_f32_e32 v101, v244, v101
	v_sub_f32_e32 v100, v243, v100
	v_sub_f32_e32 v99, v242, v99
	v_sub_f32_e32 v98, v241, v98
	v_cvt_pk_bf16_f32 v98, v98, v99
	v_cvt_pk_bf16_f32 v99, v100, v101
	ds_write_b64 v236, v[98:99] offset:4352
	s_waitcnt lgkmcnt(0)
	s_barrier
	ds_read_b128 v[98:101], v235 offset:4352
	ds_read_b128 v[106:109], v235 offset:4416
	s_waitcnt vmcnt(27) lgkmcnt(1)
	v_mfma_f32_16x16x32_bf16 v[66:69], v[66:69], v[98:101], v[102:105]
	s_waitcnt vmcnt(26) lgkmcnt(0)
	v_mfma_f32_16x16x32_bf16 v[66:69], v[74:77], v[106:109], v[66:69]
	v_mul_f32_e64 v76, v92, s66
	v_mul_f32_e64 v77, v93, s66
	v_pk_mul_f32 v[74:75], v[90:91], s[66:67] op_sel_hi:[1,0]
	v_pk_mul_f32 v[92:93], v[96:97], s[66:67] op_sel_hi:[1,0]
	v_pk_mul_f32 v[90:91], v[94:95], s[66:67] op_sel_hi:[1,0]
	s_waitcnt vmcnt(25)
	v_mfma_f32_16x16x32_bf16 v[70:73], v[70:73], v[98:101], v[74:77]
	s_waitcnt vmcnt(24)
	v_mfma_f32_16x16x32_bf16 v[122:125], v[78:81], v[106:109], v[70:73]
	s_waitcnt vmcnt(23)
	v_mfma_f32_16x16x32_bf16 v[70:73], v[82:85], v[98:101], v[90:93]
	s_waitcnt vmcnt(22)
	v_mfma_f32_16x16x32_bf16 v[126:129], v[86:89], v[106:109], v[70:73]
	s_nop 5
	v_cvt_pk_bf16_f32 v70, v122, v123
	v_cvt_pk_bf16_f32 v71, v124, v125
	v_cvt_pk_bf16_f32 v72, v126, v127
	v_cvt_pk_bf16_f32 v73, v128, v129
	ds_write2_b64 v234, v[70:71], v[72:73] offset1:4
	v_add_u32_e32 v70, 0x80, v192
	v_ashrrev_i32_e32 v71, 31, v70
	v_lshlrev_b64 v[70:71], 12, v[70:71]
	v_lshl_add_u64 v[70:71], v[190:191], 0, v[70:71]
	v_add_co_u32_e32 v72, vcc, s30, v70
	global_store_dword v[70:71], v66, off nt
	s_nop 0
	v_addc_co_u32_e32 v73, vcc, 0, v71, vcc
	v_add_co_u32_e32 v66, vcc, s31, v70
	global_store_dword v[72:73], v67, off offset:-4096 nt
	global_store_dword v[72:73], v68, off nt
	v_addc_co_u32_e32 v67, vcc, 0, v71, vcc
	global_store_dword v[66:67], v69, off nt
	v_add_co_u32_e32 v66, vcc, s46, v214
	s_waitcnt lgkmcnt(0)
	s_barrier
	ds_read_b128 v[154:157], v237
	s_nop 0
	v_addc_co_u32_e32 v67, vcc, 0, v215, vcc
	global_load_dwordx4 v[90:93], v[66:67], off
	v_add_co_u32_e32 v66, vcc, s47, v214
	s_nop 1
	v_addc_co_u32_e32 v67, vcc, 0, v215, vcc
	global_load_dwordx4 v[94:97], v[66:67], off
	v_add_co_u32_e32 v66, vcc, s46, v216
	s_nop 1
	v_addc_co_u32_e32 v67, vcc, 0, v217, vcc
	global_load_dwordx4 v[98:101], v[66:67], off
	v_add_co_u32_e32 v66, vcc, s47, v216
	s_nop 1
	v_addc_co_u32_e32 v67, vcc, 0, v217, vcc
	global_load_dwordx4 v[102:105], v[66:67], off
	v_add_co_u32_e32 v66, vcc, s46, v218
	s_nop 1
	v_addc_co_u32_e32 v67, vcc, 0, v219, vcc
	global_load_dwordx4 v[106:109], v[66:67], off
	v_add_co_u32_e32 v66, vcc, s47, v218
	s_nop 1
	v_addc_co_u32_e32 v67, vcc, 0, v219, vcc
	global_load_dwordx4 v[110:113], v[66:67], off
	v_add_co_u32_e32 v66, vcc, s46, v220
	s_nop 1
	v_addc_co_u32_e32 v67, vcc, 0, v221, vcc
	global_load_dwordx4 v[114:117], v[66:67], off
	v_add_co_u32_e32 v66, vcc, s47, v220
	s_nop 1
	v_addc_co_u32_e32 v67, vcc, 0, v221, vcc
	global_load_dwordx4 v[118:121], v[66:67], off
	v_add_co_u32_e32 v66, vcc, s48, v222
	s_nop 1
	v_addc_co_u32_e32 v67, vcc, 0, v223, vcc
	global_load_dword v241, v[66:67], off
	global_load_dword v242, v[66:67], off offset:256
	global_load_dword v243, v[66:67], off offset:512
	global_load_dword v244, v[66:67], off offset:768
	v_add_co_u32_e32 v66, vcc, s49, v224
	s_nop 1
	v_addc_co_u32_e32 v67, vcc, 0, v225, vcc
	v_add_co_u32_e32 v70, vcc, s49, v226
	global_load_dwordx4 v[66:69], v[66:67], off
	s_nop 0
	v_addc_co_u32_e32 v71, vcc, 0, v227, vcc
	v_add_co_u32_e32 v82, vcc, s50, v228
	global_load_dwordx4 v[74:77], v[70:71], off
	s_nop 0
	v_addc_co_u32_e32 v83, vcc, 0, v229, vcc
	v_add_co_u32_e32 v78, vcc, s50, v230
	global_load_dwordx4 v[70:73], v[82:83], off
	s_nop 0
	v_addc_co_u32_e32 v79, vcc, 0, v231, vcc
	global_load_dwordx4 v[78:81], v[78:79], off
	s_nop 0
	global_load_dwordx4 v[82:85], v[82:83], off offset:1024

	s_waitcnt lgkmcnt(0)
	v_mfma_f32_16x16x32_bf16 v[2:5], v[2:5], v[154:157], 0
	v_add_co_u32_e32 v86, vcc, s50, v232
	v_mfma_f32_16x16x32_bf16 v[6:9], v[6:9], v[154:157], 0
	ds_read_b128 v[154:157], v237 offset:64
	v_addc_co_u32_e32 v87, vcc, 0, v233, vcc
	s_waitcnt lgkmcnt(0)
	v_mfma_f32_16x16x32_bf16 v[2:5], v[10:13], v[154:157], v[2:5]
	ds_read_b128 v[10:13], v237 offset:128
	global_load_dwordx4 v[86:89], v[86:87], off
	v_mfma_f32_16x16x32_bf16 v[6:9], v[14:17], v[154:157], v[6:9]
	s_waitcnt lgkmcnt(0)
	v_mfma_f32_16x16x32_bf16 v[2:5], v[18:21], v[10:13], v[2:5]
	v_mul_f32_e64 v20, v128, s64
	v_mul_f32_e64 v21, v129, s64
	v_pk_mul_f32 v[18:19], v[126:127], s[64:65] op_sel_hi:[1,0]
	v_mfma_f32_16x16x32_bf16 v[6:9], v[22:25], v[10:13], v[6:9]
	ds_read_b128 v[10:13], v237 offset:192
	s_waitcnt lgkmcnt(0)
	v_mfma_f32_16x16x32_bf16 v[2:5], v[26:29], v[10:13], v[2:5]
	v_mfma_f32_16x16x32_bf16 v[6:9], v[38:41], v[10:13], v[6:9]
	s_nop 6
	v_sub_f32_e32 v5, v240, v5
	v_sub_f32_e32 v4, v239, v4
	v_sub_f32_e32 v3, v238, v3
	v_sub_f32_e32 v2, v193, v2
	v_cvt_pk_bf16_f32 v2, v2, v3
	v_cvt_pk_bf16_f32 v3, v4, v5
	ds_write_b64 v236, v[2:3] offset:4352
	s_waitcnt lgkmcnt(0)
	s_barrier
	ds_read_b128 v[10:13], v235 offset:4352
	ds_read_b128 v[14:17], v235 offset:4416
	s_waitcnt vmcnt(27) lgkmcnt(1)
	v_mfma_f32_16x16x32_bf16 v[2:5], v[130:133], v[10:13], v[6:9]
	s_nop 2
	v_mul_f32_e64 v8, v124, s64
	v_mul_f32_e64 v9, v125, s64
	v_pk_mul_f32 v[6:7], v[122:123], s[64:65] op_sel_hi:[1,0]
	v_readlane_b32 s64, v177, s65
	s_waitcnt vmcnt(26) lgkmcnt(0)
	v_mfma_f32_16x16x32_bf16 v[2:5], v[138:141], v[14:17], v[2:5]
	s_waitcnt vmcnt(25)
	v_mfma_f32_16x16x32_bf16 v[6:9], v[134:137], v[10:13], v[6:9]
	s_waitcnt vmcnt(24)
	v_mfma_f32_16x16x32_bf16 v[154:157], v[142:145], v[14:17], v[6:9]
	s_waitcnt vmcnt(23)
	v_mfma_f32_16x16x32_bf16 v[6:9], v[146:149], v[10:13], v[18:21]
	s_waitcnt vmcnt(22)
	v_mfma_f32_16x16x32_bf16 v[146:149], v[150:153], v[14:17], v[6:9]
	s_nop 5
	v_cvt_pk_bf16_f32 v6, v154, v155
	v_cvt_pk_bf16_f32 v7, v156, v157
	v_cvt_pk_bf16_f32 v8, v146, v147
	v_cvt_pk_bf16_f32 v9, v148, v149
	ds_write2_b64 v234, v[6:7], v[8:9] offset1:4
	v_add_u32_e32 v6, 0xc0, v192
	v_ashrrev_i32_e32 v7, 31, v6
	v_lshlrev_b64 v[6:7], 12, v[6:7]
	v_lshl_add_u64 v[6:7], v[190:191], 0, v[6:7]
	v_add_co_u32_e32 v8, vcc, s30, v6
	global_store_dword v[6:7], v2, off nt
	s_nop 0
	v_addc_co_u32_e32 v9, vcc, 0, v7, vcc
	v_add_co_u32_e32 v2, vcc, s31, v6
	global_store_dword v[8:9], v3, off offset:-4096 nt
	global_store_dword v[8:9], v4, off nt
	v_addc_co_u32_e32 v3, vcc, 0, v7, vcc
	global_store_dword v[2:3], v5, off nt
	v_add_co_u32_e32 v2, vcc, s51, v214
	s_waitcnt lgkmcnt(0)
	s_barrier
	ds_read_b128 v[150:153], v237
	s_nop 0
	v_addc_co_u32_e32 v3, vcc, 0, v215, vcc
	global_load_dwordx4 v[18:21], v[2:3], off
	v_add_co_u32_e32 v2, vcc, s52, v214
	s_nop 1
	v_addc_co_u32_e32 v3, vcc, 0, v215, vcc
	global_load_dwordx4 v[38:41], v[2:3], off
	v_add_co_u32_e32 v2, vcc, s51, v216
	s_nop 1
	v_addc_co_u32_e32 v3, vcc, 0, v217, vcc
	global_load_dwordx4 v[6:9], v[2:3], off
	v_add_co_u32_e32 v2, vcc, s52, v216
	s_nop 1
	v_addc_co_u32_e32 v3, vcc, 0, v217, vcc
	v_add_co_u32_e32 v10, vcc, s51, v218
	global_load_dwordx4 v[2:5], v[2:3], off
	s_nop 0
	v_addc_co_u32_e32 v11, vcc, 0, v219, vcc
	global_load_dwordx4 v[26:29], v[10:11], off
	v_add_co_u32_e32 v10, vcc, s52, v218
	s_nop 1
	v_addc_co_u32_e32 v11, vcc, 0, v219, vcc
	global_load_dwordx4 v[14:17], v[10:11], off
	v_add_co_u32_e32 v10, vcc, s51, v220
	s_nop 1
	v_addc_co_u32_e32 v11, vcc, 0, v221, vcc
	global_load_dwordx4 v[22:25], v[10:11], off
	v_add_co_u32_e32 v10, vcc, s52, v220
	s_nop 1
	v_addc_co_u32_e32 v11, vcc, 0, v221, vcc
	v_add_co_u32_e32 v122, vcc, s53, v222
	global_load_dwordx4 v[10:13], v[10:11], off
	s_nop 0
	v_addc_co_u32_e32 v123, vcc, 0, v223, vcc
	global_load_dword v193, v[122:123], off
	global_load_dword v238, v[122:123], off offset:256
	global_load_dword v239, v[122:123], off offset:512
	global_load_dword v240, v[122:123], off offset:768
	v_add_co_u32_e32 v122, vcc, s54, v224
	s_nop 1
	v_addc_co_u32_e32 v123, vcc, 0, v225, vcc
	v_add_co_u32_e32 v126, vcc, s54, v226
	global_load_dwordx4 v[122:125], v[122:123], off
	s_nop 0
	v_addc_co_u32_e32 v127, vcc, 0, v227, vcc
	v_add_co_u32_e32 v138, vcc, s55, v228
	global_load_dwordx4 v[130:133], v[126:127], off
	s_nop 0
	v_addc_co_u32_e32 v139, vcc, 0, v229, vcc
	v_add_co_u32_e32 v134, vcc, s55, v230
	global_load_dwordx4 v[126:129], v[138:139], off
	s_nop 0
	v_addc_co_u32_e32 v135, vcc, 0, v231, vcc
	global_load_dwordx4 v[134:137], v[134:135], off
	s_nop 0
	global_load_dwordx4 v[138:141], v[138:139], off offset:1024

	s_waitcnt lgkmcnt(0)
	v_mfma_f32_16x16x32_bf16 v[30:33], v[30:33], v[150:153], 0
	v_add_co_u32_e32 v142, vcc, s55, v232
	v_mfma_f32_16x16x32_bf16 v[34:37], v[34:37], v[150:153], 0
	ds_read_b128 v[150:153], v237 offset:64
	v_addc_co_u32_e32 v143, vcc, 0, v233, vcc
	s_waitcnt lgkmcnt(0)
	v_mfma_f32_16x16x32_bf16 v[30:33], v[42:45], v[150:153], v[30:33]
	ds_read_b128 v[42:45], v237 offset:128
	global_load_dwordx4 v[142:145], v[142:143], off
	v_mfma_f32_16x16x32_bf16 v[34:37], v[46:49], v[150:153], v[34:37]
	s_waitcnt lgkmcnt(0)
	v_mfma_f32_16x16x32_bf16 v[30:33], v[50:53], v[42:45], v[30:33]
	v_mul_f32_e64 v52, v148, s64
	v_mul_f32_e64 v53, v149, s64
	v_pk_mul_f32 v[50:51], v[146:147], s[64:65] op_sel_hi:[1,0]
	v_mfma_f32_16x16x32_bf16 v[34:37], v[54:57], v[42:45], v[34:37]
	ds_read_b128 v[42:45], v237 offset:192
	s_waitcnt lgkmcnt(0)
	v_mfma_f32_16x16x32_bf16 v[30:33], v[58:61], v[42:45], v[30:33]
	v_mfma_f32_16x16x32_bf16 v[34:37], v[62:65], v[42:45], v[34:37]
	s_nop 6
	v_sub_f32_e32 v33, v248, v33
	v_sub_f32_e32 v32, v247, v32
	v_sub_f32_e32 v31, v246, v31
	v_sub_f32_e32 v30, v245, v30
	v_cvt_pk_bf16_f32 v30, v30, v31
	v_cvt_pk_bf16_f32 v31, v32, v33
	ds_write_b64 v236, v[30:31] offset:4352
	s_waitcnt lgkmcnt(0)
	s_barrier
	ds_read_b128 v[42:45], v235 offset:4352
	ds_read_b128 v[46:49], v235 offset:4416
	s_waitcnt vmcnt(27) lgkmcnt(1)
	v_mfma_f32_16x16x32_bf16 v[30:33], v[66:69], v[42:45], v[34:37]
	s_nop 2
	v_mul_f32_e64 v36, v156, s64
	v_mul_f32_e64 v37, v157, s64
	v_pk_mul_f32 v[34:35], v[154:155], s[64:65] op_sel_hi:[1,0]
	s_waitcnt vmcnt(26) lgkmcnt(0)
	v_mfma_f32_16x16x32_bf16 v[30:33], v[74:77], v[46:49], v[30:33]
	s_waitcnt vmcnt(25)
	v_mfma_f32_16x16x32_bf16 v[34:37], v[70:73], v[42:45], v[34:37]
	s_waitcnt vmcnt(24)
	v_mfma_f32_16x16x32_bf16 v[146:149], v[78:81], v[46:49], v[34:37]
	s_waitcnt vmcnt(23)
	v_mfma_f32_16x16x32_bf16 v[34:37], v[82:85], v[42:45], v[50:53]
	s_waitcnt vmcnt(22)
	v_mfma_f32_16x16x32_bf16 v[150:153], v[86:89], v[46:49], v[34:37]
	s_nop 5
	v_cvt_pk_bf16_f32 v34, v146, v147
	v_cvt_pk_bf16_f32 v35, v148, v149
	v_cvt_pk_bf16_f32 v36, v150, v151
	v_cvt_pk_bf16_f32 v37, v152, v153
	ds_write2_b64 v234, v[34:35], v[36:37] offset1:4
	v_add_u32_e32 v34, 0x100, v192
	v_ashrrev_i32_e32 v35, 31, v34
	v_lshlrev_b64 v[34:35], 12, v[34:35]
	v_lshl_add_u64 v[34:35], v[190:191], 0, v[34:35]
	v_add_co_u32_e32 v36, vcc, s30, v34
	global_store_dword v[34:35], v30, off nt
	s_nop 0
	v_addc_co_u32_e32 v37, vcc, 0, v35, vcc
	v_add_co_u32_e32 v30, vcc, s31, v34
	global_store_dword v[36:37], v31, off offset:-4096 nt
	global_store_dword v[36:37], v32, off nt
	v_addc_co_u32_e32 v31, vcc, 0, v35, vcc
	global_store_dword v[30:31], v33, off nt
	v_add_co_u32_e32 v30, vcc, s56, v214
	s_waitcnt lgkmcnt(0)
	s_barrier
	s_nop 0
	v_addc_co_u32_e32 v31, vcc, 0, v215, vcc
	v_add_co_u32_e32 v34, vcc, s57, v214
	global_load_dwordx4 v[30:33], v[30:31], off
	s_nop 0
	v_addc_co_u32_e32 v35, vcc, 0, v215, vcc
	v_add_co_u32_e32 v42, vcc, s56, v216
	global_load_dwordx4 v[34:37], v[34:35], off
	s_nop 0
	v_addc_co_u32_e32 v43, vcc, 0, v217, vcc
	global_load_dwordx4 v[46:49], v[42:43], off
	v_add_co_u32_e32 v42, vcc, s57, v216
	s_nop 1
	v_addc_co_u32_e32 v43, vcc, 0, v217, vcc
	ds_read_b128 v[214:217], v237
	global_load_dwordx4 v[50:53], v[42:43], off
	v_add_co_u32_e32 v42, vcc, s56, v218
	s_nop 1
	v_addc_co_u32_e32 v43, vcc, 0, v219, vcc
	v_add_co_u32_e32 v54, vcc, s57, v218
	global_load_dwordx4 v[42:45], v[42:43], off
	s_nop 0
	v_addc_co_u32_e32 v55, vcc, 0, v219, vcc
	v_add_co_u32_e32 v58, vcc, s56, v220
	global_load_dwordx4 v[54:57], v[54:55], off
	s_nop 0
	v_addc_co_u32_e32 v59, vcc, 0, v221, vcc
	v_add_co_u32_e32 v62, vcc, s57, v220
	global_load_dwordx4 v[58:61], v[58:59], off
	s_nop 0
	v_addc_co_u32_e32 v63, vcc, 0, v221, vcc
	v_add_co_u32_e32 v66, vcc, s58, v222
	global_load_dwordx4 v[62:65], v[62:63], off
	s_nop 0
	v_addc_co_u32_e32 v67, vcc, 0, v223, vcc
	global_load_dword v157, v[66:67], off
	global_load_dword v154, v[66:67], off offset:256
	global_load_dword v155, v[66:67], off offset:512
	global_load_dword v156, v[66:67], off offset:768
	v_add_co_u32_e32 v66, vcc, s59, v224
	s_nop 1
	v_addc_co_u32_e32 v67, vcc, 0, v225, vcc
	global_load_dwordx4 v[86:89], v[66:67], off
	v_add_co_u32_e32 v66, vcc, s59, v226
	s_nop 1
	v_addc_co_u32_e32 v67, vcc, 0, v227, vcc
	global_load_dwordx4 v[74:77], v[66:67], off
	v_add_co_u32_e32 v66, vcc, s60, v228
	s_nop 1
	v_addc_co_u32_e32 v67, vcc, 0, v229, vcc
	v_add_co_u32_e32 v68, vcc, s60, v230
	global_load_dwordx4 v[70:73], v[66:67], off
	s_nop 0
	v_addc_co_u32_e32 v69, vcc, 0, v231, vcc
	v_add_co_u32_e32 v78, vcc, s60, v232
	global_load_dwordx4 v[82:85], v[68:69], off
	s_nop 0
	global_load_dwordx4 v[66:69], v[66:67], off offset:1024
	v_addc_co_u32_e32 v79, vcc, 0, v233, vcc
	global_load_dwordx4 v[78:81], v[78:79], off

; DEV void gdn_scan_item(const Params& p, int item, unsigned char* lds) {
;     ...
;     LOAD_E(E0, 0); LOAD_L(L0, 0); LOAD_E(E1, 1);
;     __syncthreads();
;     for (int ch = 0; ch < 30; ch += 6) {
;         SCAN_STEP(E0, E2, L0, L1, ch);     SCAN_STEP(E1, E0, L1, L0, ch + 1); SCAN_STEP(E2, E1, L0, L1, ch + 2);
;         SCAN_STEP(E0, E2, L1, L0, ch + 3); SCAN_STEP(E1, E0, L0, L1, ch + 4); SCAN_STEP(E2, E1, L1, L0, ch + 5);
;     }
;     SCAN_STEP(E0, E2, L0, L1, 30); SCAN_STEP(E1, E0, L1, L0, 31);
	s_waitcnt lgkmcnt(0)
	v_mfma_f32_16x16x32_bf16 v[90:93], v[90:93], v[214:217], 0
	v_mfma_f32_16x16x32_bf16 v[94:97], v[94:97], v[214:217], 0
	ds_read_b128 v[214:217], v237 offset:64
	s_waitcnt lgkmcnt(0)
	v_mfma_f32_16x16x32_bf16 v[90:93], v[98:101], v[214:217], v[90:93]
	ds_read_b128 v[98:101], v237 offset:128
	v_mfma_f32_16x16x32_bf16 v[94:97], v[102:105], v[214:217], v[94:97]
	s_waitcnt lgkmcnt(0)
	v_mfma_f32_16x16x32_bf16 v[90:93], v[106:109], v[98:101], v[90:93]
	v_mul_f32_e64 v108, v152, s62
	v_mul_f32_e64 v109, v153, s62
	v_pk_mul_f32 v[106:107], v[150:151], s[62:63] op_sel_hi:[1,0]
	v_mfma_f32_16x16x32_bf16 v[94:97], v[110:113], v[98:101], v[94:97]
	ds_read_b128 v[98:101], v237 offset:192
	s_waitcnt lgkmcnt(0)
	v_mfma_f32_16x16x32_bf16 v[90:93], v[114:117], v[98:101], v[90:93]
	v_mfma_f32_16x16x32_bf16 v[94:97], v[118:121], v[98:101], v[94:97]
	s_nop 6
	v_sub_f32_e32 v93, v244, v93
	v_sub_f32_e32 v92, v243, v92
	v_sub_f32_e32 v91, v242, v91
	v_sub_f32_e32 v90, v241, v90
	v_cvt_pk_bf16_f32 v90, v90, v91
	v_cvt_pk_bf16_f32 v91, v92, v93
	ds_write_b64 v236, v[90:91] offset:4352
	s_waitcnt lgkmcnt(0)
	s_barrier
	ds_read_b128 v[90:93], v235 offset:4352
	ds_read_b128 v[102:105], v235 offset:4416
	s_waitcnt vmcnt(27) lgkmcnt(1)
	v_mfma_f32_16x16x32_bf16 v[94:97], v[122:125], v[90:93], v[94:97]
	s_waitcnt vmcnt(26) lgkmcnt(0)
	v_mfma_f32_16x16x32_bf16 v[98:101], v[130:133], v[102:105], v[94:97]
	s_nop 5
	v_mul_f32_e64 v96, v148, s62
	v_mul_f32_e64 v97, v149, s62
	v_pk_mul_f32 v[94:95], v[146:147], s[62:63] op_sel_hi:[1,0]
	s_mov_b32 s62, s61
	s_waitcnt vmcnt(25)
	v_mfma_f32_16x16x32_bf16 v[94:97], v[126:129], v[90:93], v[94:97]
	s_waitcnt vmcnt(23)
	v_mfma_f32_16x16x32_bf16 v[90:93], v[138:141], v[90:93], v[106:109]
	v_mfma_f32_16x16x32_bf16 v[94:97], v[134:137], v[102:105], v[94:97]
	s_waitcnt vmcnt(22)
	v_mfma_f32_16x16x32_bf16 v[90:93], v[142:145], v[102:105], v[90:93]
	s_nop 5
	v_cvt_pk_bf16_f32 v102, v94, v95
	v_cvt_pk_bf16_f32 v103, v96, v97
	v_cvt_pk_bf16_f32 v104, v90, v91
	v_cvt_pk_bf16_f32 v105, v92, v93
	ds_write2_b64 v234, v[102:103], v[104:105] offset1:4
	v_add_u32_e32 v102, 0x140, v192
	v_ashrrev_i32_e32 v103, 31, v102
	v_lshlrev_b64 v[102:103], 12, v[102:103]
	v_lshl_add_u64 v[102:103], v[190:191], 0, v[102:103]
	v_add_co_u32_e32 v104, vcc, s30, v102
	global_store_dword v[102:103], v98, off nt
	s_nop 0
	v_addc_co_u32_e32 v105, vcc, 0, v103, vcc
	v_add_co_u32_e32 v98, vcc, s31, v102
	global_store_dword v[104:105], v99, off offset:-4096 nt
	global_store_dword v[104:105], v100, off nt
	v_addc_co_u32_e32 v99, vcc, 0, v103, vcc
	global_store_dword v[98:99], v101, off nt
	s_waitcnt lgkmcnt(0)
	s_barrier
	v_add_u32_e32 v192, 0x180, v192
	s_cbranch_scc1 .LBB0_888
	ds_read_b128 v[98:101], v237
	ds_read_b128 v[102:105], v237 offset:64
	s_add_u32 s8, s12, 0x3e000
	s_addc_u32 s9, s13, 0
	v_lshl_add_u64 v[106:107], s[8:9], 0, v[180:181]
	s_waitcnt lgkmcnt(1)
	v_mfma_f32_16x16x32_bf16 v[18:21], v[18:21], v[98:101], 0
	v_or_b32_e32 v108, 0x400, v184
	v_add3_u32 v1, v1, s24, v179
	s_movk_i32 s13, 0x2000
	v_mfma_f32_16x16x32_bf16 v[38:41], v[38:41], v[98:101], 0
	v_lshl_add_u64 v[98:99], s[8:9], 0, v[182:183]
	s_add_u32 s8, s10, 0x7c000
	s_addc_u32 s9, s11, 0
	s_waitcnt lgkmcnt(0)
	v_mfma_f32_16x16x32_bf16 v[6:9], v[6:9], v[102:105], v[18:21]
	v_lshl_add_u64 v[100:101], s[8:9], 0, v[184:185]
	v_lshl_add_u64 v[110:111], s[8:9], 0, v[188:189]
	s_lshl_b32 s10, s23, 2
	ds_read_b128 v[18:21], v237 offset:128
	v_mfma_f32_16x16x32_bf16 v[2:5], v[2:5], v[102:105], v[38:41]
	s_nop 2
	global_load_dwordx4 v[38:41], v[98:99], off
	s_nop 0
	global_load_dwordx4 v[98:101], v[100:101], off
	ds_read_b128 v[102:105], v237 offset:192
	s_movk_i32 s16, 0x3000
	s_waitcnt lgkmcnt(1)
	v_mfma_f32_16x16x32_bf16 v[6:9], v[26:29], v[18:21], v[6:9]
	global_load_dwordx4 v[26:29], v[106:107], off
	s_nop 0
	global_load_dwordx4 v[106:109], v108, s[8:9]
	v_readlane_b32 s12, v177, 31
	s_lshl_b64 s[4:5], s[4:5], 7
	v_mfma_f32_16x16x32_bf16 v[2:5], v[14:17], v[18:21], v[2:5]
	v_lshl_add_u64 v[18:19], s[8:9], 0, v[186:187]
	global_load_dwordx4 v[14:17], v[110:111], off
	s_nop 0
	global_load_dwordx4 v[18:21], v[18:19], off
	v_readlane_b32 s8, v177, 30
	s_waitcnt lgkmcnt(0)
	v_mfma_f32_16x16x32_bf16 v[6:9], v[22:25], v[102:105], v[6:9]
	v_ashrrev_i32_e32 v177, 31, v176
	v_pk_mul_f32 v[24:25], v[96:97], s[8:9] op_sel_hi:[1,0]
	v_pk_mul_f32 v[22:23], v[94:95], s[8:9] op_sel_hi:[1,0]
	v_mfma_f32_16x16x32_bf16 v[2:5], v[10:13], v[102:105], v[2:5]
	s_nop 3
	v_sub_f32_e32 v9, v240, v9
	v_sub_f32_e32 v8, v239, v8
	v_sub_f32_e32 v7, v238, v7
	v_sub_f32_e32 v6, v193, v6
	v_cvt_pk_bf16_f32 v6, v6, v7
	v_cvt_pk_bf16_f32 v7, v8, v9
	ds_write_b64 v236, v[6:7] offset:4352
	s_waitcnt lgkmcnt(0)
	s_barrier
; DEV void gdn_scan_item(const Params& p, int item, unsigned char* lds) {
;     ...
;     LOAD_E(E0, 0); LOAD_L(L0, 0); LOAD_E(E1, 1);
;     __syncthreads();
;     for (int ch = 0; ch < 30; ch += 6) {
;         SCAN_STEP(E0, E2, L0, L1, ch);     SCAN_STEP(E1, E0, L1, L0, ch + 1); SCAN_STEP(E2, E1, L0, L1, ch + 2);
;         SCAN_STEP(E0, E2, L1, L0, ch + 3); SCAN_STEP(E1, E0, L0, L1, ch + 4); SCAN_STEP(E2, E1, L1, L0, ch + 5);
;     }
;     SCAN_STEP(E0, E2, L0, L1, 30); SCAN_STEP(E1, E0, L1, L0, 31);
;     ...
;     {
;         float* dp = p.out + O_DP + ((size_t)bh * 128 + w * 32 + fq * 4) * 128 + s * 16 + fr;
; #pragma unroll
;         for (int e = 0; e < 4; ++e) { dp[e * 128] = S0[e]; dp[(16 + e) * 128] = S1[e]; }
;     }
;     __syncthreads();
	ds_read_b128 v[6:9], v235 offset:4352
	ds_read_b128 v[10:13], v235 offset:4416
	s_waitcnt vmcnt(13) lgkmcnt(1)
	v_mfma_f32_16x16x32_bf16 v[22:25], v[70:73], v[6:9], v[22:25]
	v_mul_f32_e64 v72, v92, s8
	v_mul_f32_e64 v73, v93, s8
	v_pk_mul_f32 v[70:71], v[90:91], s[8:9] op_sel_hi:[1,0]
	s_mov_b32 s9, 0
	v_mfma_f32_16x16x32_bf16 v[2:5], v[86:89], v[6:9], v[2:5]
	s_lshl_b32 s8, s22, 2
	s_mov_b32 s11, s9
	s_waitcnt vmcnt(11)
	v_mfma_f32_16x16x32_bf16 v[6:9], v[66:69], v[6:9], v[70:73]
	s_waitcnt lgkmcnt(0)
	v_mfma_f32_16x16x32_bf16 v[22:25], v[82:85], v[10:13], v[22:25]
	s_waitcnt vmcnt(10)
	v_mfma_f32_16x16x32_bf16 v[6:9], v[78:81], v[10:13], v[6:9]
	v_mfma_f32_16x16x32_bf16 v[2:5], v[74:77], v[10:13], v[2:5]
	v_add_u32_e32 v10, 0x780, v1
	v_ashrrev_i32_e32 v11, 31, v10
	v_lshlrev_b64 v[10:11], 12, v[10:11]
	v_lshl_add_u64 v[10:11], s[6:7], 0, v[10:11]
	s_nop 0
	v_cvt_pk_bf16_f32 v66, v22, v23
	v_cvt_pk_bf16_f32 v67, v24, v25
	v_cvt_pk_bf16_f32 v68, v6, v7
	v_cvt_pk_bf16_f32 v69, v8, v9
	v_lshl_add_u64 v[10:11], v[10:11], 0, s[8:9]
	ds_write2_b64 v234, v[66:67], v[68:69] offset1:4
	v_lshl_add_u64 v[10:11], v[10:11], 0, s[10:11]
	v_lshlrev_b32_e32 v66, 2, v178
	v_mov_b32_e32 v67, 0
	v_lshl_add_u64 v[10:11], v[10:11], 0, v[66:67]
	v_add_co_u32_e32 v12, vcc, s13, v10
	global_store_dword v[10:11], v2, off nt
	s_nop 0
	v_addc_co_u32_e32 v13, vcc, 0, v11, vcc
	v_add_co_u32_e32 v2, vcc, s16, v10
	global_store_dword v[12:13], v3, off offset:-4096 nt
	global_store_dword v[12:13], v4, off nt
	v_addc_co_u32_e32 v3, vcc, 0, v11, vcc
	global_store_dword v[2:3], v5, off nt
	s_waitcnt lgkmcnt(0)
	s_barrier
	ds_read_b128 v[2:5], v237
	ds_read_b128 v[10:13], v237 offset:64
	s_waitcnt lgkmcnt(1)
	v_mfma_f32_16x16x32_bf16 v[30:33], v[30:33], v[2:5], 0
	v_mul_f32_e64 v24, v24, s12
	v_mul_f32_e64 v25, v25, s12
	v_pk_mul_f32 v[22:23], v[22:23], s[12:13] op_sel_hi:[1,0]
	v_pk_mul_f32 v[8:9], v[8:9], s[12:13] op_sel_hi:[1,0]
	v_mfma_f32_16x16x32_bf16 v[2:5], v[34:37], v[2:5], 0
	v_mul_f32_e64 v6, v6, s12
	v_mul_f32_e64 v7, v7, s12
	s_waitcnt lgkmcnt(0)
	v_mfma_f32_16x16x32_bf16 v[30:33], v[46:49], v[10:13], v[30:33]
	v_mfma_f32_16x16x32_bf16 v[2:5], v[50:53], v[10:13], v[2:5]
	ds_read_b128 v[10:13], v237 offset:128
	ds_read_b128 v[34:37], v237 offset:192
	s_waitcnt lgkmcnt(1)
	v_mfma_f32_16x16x32_bf16 v[30:33], v[42:45], v[10:13], v[30:33]
	v_mfma_f32_16x16x32_bf16 v[2:5], v[54:57], v[10:13], v[2:5]
	s_waitcnt lgkmcnt(0)
	v_mfma_f32_16x16x32_bf16 v[10:13], v[58:61], v[34:37], v[30:33]
	v_mfma_f32_16x16x32_bf16 v[2:5], v[62:65], v[34:37], v[2:5]
	s_nop 6
	v_sub_f32_e32 v13, v156, v13
	v_sub_f32_e32 v12, v155, v12
	v_sub_f32_e32 v11, v154, v11
	v_sub_f32_e32 v10, v157, v10
	v_cvt_pk_bf16_f32 v10, v10, v11
	v_cvt_pk_bf16_f32 v11, v12, v13
	ds_write_b64 v236, v[10:11] offset:4352
	s_waitcnt lgkmcnt(0)
	s_barrier
	ds_read_b128 v[10:13], v235 offset:4352
	ds_read_b128 v[30:33], v235 offset:4416
	s_waitcnt vmcnt(8) lgkmcnt(1)
	v_mfma_f32_16x16x32_bf16 v[22:25], v[98:101], v[10:13], v[22:25]
	s_waitcnt vmcnt(6)
	v_mfma_f32_16x16x32_bf16 v[6:9], v[106:109], v[10:13], v[6:9]
	s_waitcnt vmcnt(5) lgkmcnt(0)
	v_mfma_f32_16x16x32_bf16 v[14:17], v[14:17], v[30:33], v[22:25]
	s_waitcnt vmcnt(4)
	v_mfma_f32_16x16x32_bf16 v[6:9], v[18:21], v[30:33], v[6:9]
	v_mfma_f32_16x16x32_bf16 v[2:5], v[26:29], v[10:13], v[2:5]
	s_nop 4
	v_cvt_pk_bf16_f32 v10, v14, v15
	v_cvt_pk_bf16_f32 v11, v16, v17
	v_cvt_pk_bf16_f32 v12, v6, v7
	v_cvt_pk_bf16_f32 v13, v8, v9
	ds_write2_b64 v234, v[10:11], v[12:13] offset1:4
	v_add_u32_e32 v10, 0x7c0, v1
	v_ashrrev_i32_e32 v11, 31, v10
	v_lshlrev_b64 v[10:11], 12, v[10:11]
	v_lshl_add_u64 v[10:11], s[6:7], 0, v[10:11]
	v_lshl_add_u64 v[10:11], v[10:11], 0, s[8:9]
	v_mfma_f32_16x16x32_bf16 v[2:5], v[38:41], v[30:33], v[2:5]
	v_lshl_add_u64 v[10:11], v[10:11], 0, s[10:11]
	v_lshl_add_u64 v[10:11], v[10:11], 0, v[66:67]
	v_add_co_u32_e32 v12, vcc, s13, v10
	s_nop 1
	v_addc_co_u32_e32 v13, vcc, 0, v11, vcc
	s_nop 1
	global_store_dword v[10:11], v2, off nt
	v_add_co_u32_e32 v2, vcc, s16, v10
	global_store_dword v[12:13], v3, off offset:-4096 nt
	global_store_dword v[12:13], v4, off nt
	v_addc_co_u32_e32 v3, vcc, 0, v11, vcc
	global_store_dword v[2:3], v5, off nt
	s_waitcnt lgkmcnt(0)
	s_barrier
	s_load_dwordx2 s[6:7], s[0:1], 0xc0
	v_lshl_add_u64 v[2:3], s[4:5], 0, v[176:177]
	v_or_b32_e32 v2, v2, v179
	v_lshlrev_b64 v[2:3], 9, v[2:3]
	s_mov_b64 s[4:5], 0x5400000
	s_waitcnt lgkmcnt(0)
	v_lshl_add_u64 v[2:3], s[6:7], 0, v[2:3]
	v_lshl_add_u64 v[2:3], v[2:3], 0, s[10:11]
	v_lshl_add_u64 v[2:3], v[2:3], 0, v[66:67]
	v_lshl_add_u64 v[4:5], v[2:3], 0, s[4:5]
	s_mov_b32 s4, 0x5400000
	v_add_co_u32_e32 v10, vcc, s4, v2
	s_nop 1
	v_addc_co_u32_e32 v11, vcc, 0, v3, vcc
	v_add_co_u32_e32 v2, vcc, 0x5402000, v2
	global_store_dword v[10:11], v14, off nt
	s_nop 0
	v_addc_co_u32_e32 v3, vcc, 0, v3, vcc
	global_store_dword v[2:3], v6, off nt
	global_store_dword v[4:5], v15, off offset:512 nt
	global_store_dword v[2:3], v7, off offset:512 nt
	global_store_dword v[4:5], v16, off offset:1024 nt
	global_store_dword v[2:3], v8, off offset:1024 nt
	global_store_dword v[4:5], v17, off offset:1536 nt
	global_store_dword v[2:3], v9, off offset:1536 nt
	s_barrier
